# grid-barrier / queue poll loops: s_sleep 1 shortened to s_sleep 0 (on top of v54)
# speedup vs baseline: 1.0112x; 1.0112x over previous
; __global__ void __launch_bounds__(512, 2) hybrid_fwd(Params p) {
;     ...
;     if (p.sinks[0] > 1.0e30f) grid.sync();
.LBB0_14:
	s_sleep 0
	global_load_dword v2, v0, s[10:11] offset:32 sc1
	s_waitcnt vmcnt(0)
	v_and_b32_e32 v2, 0xffff0000, v2
	v_cmp_ne_u32_e32 vcc, v2, v1
	s_or_b64 s[12:13], vcc, s[12:13]
	s_andn2_b64 exec, exec, s[12:13]
	s_cbranch_execnz .LBB0_14

; DI unsigned xb_ld(unsigned* p)              { return __hip_atomic_load(p, __ATOMIC_RELAXED, __HIP_MEMORY_SCOPE_AGENT); }
; DI void xcd_barrier_complete(unsigned* bar, unsigned x, unsigned& nloc, unsigned& nx) {
;     ...
;     for (;;) {
;         sum = 0u; cnt = 0u; mine = 0u;
; #pragma unroll
;         for (unsigned j = 0; j < 16; ++j) { const unsigned c = xb_ld(&bar[XB_XCNT(j)]); sum += c; cnt += (c > 0u) ? 1u : 0u; mine = (j == x) ? c : mine; }
;         if (sum == G) break;
;         __builtin_amdgcn_s_sleep(1);
;         if ((++sp & 255u) == 0u) { if (xb_ld(&bar[XB_TMO])) break; if (sp > XB_SPIN_CAP) { atomicAdd(&bar[XB_TMO], 1u); break; } }
;     }
.LBB0_135:
	global_load_dword v15, v16, s[10:11] sc1
	s_waitcnt lgkmcnt(0)
	global_load_dword v0, v16, s[12:13] sc1
	global_load_dword v1, v16, s[14:15] sc1
	global_load_dword v2, v16, s[16:17] sc1
	global_load_dword v3, v16, s[18:19] sc1
	global_load_dword v4, v16, s[20:21] sc1
	global_load_dword v5, v16, s[22:23] sc1
	global_load_dword v6, v16, s[24:25] sc1
	global_load_dword v7, v16, s[26:27] sc1
	global_load_dword v8, v16, s[28:29] sc1
	global_load_dword v9, v16, s[30:31] sc1
	global_load_dword v10, v16, s[34:35] sc1
	global_load_dword v11, v16, s[36:37] sc1
	global_load_dword v12, v16, s[38:39] sc1
	global_load_dword v13, v16, s[40:41] sc1
	global_load_dword v14, v16, s[42:43] sc1
	s_mov_b64 s[44:45], -1
	s_mov_b64 s[46:47], -1
	s_waitcnt vmcnt(14)
	v_add_u32_e32 v17, v0, v15
	s_waitcnt vmcnt(13)
	v_add_u32_e32 v17, v17, v1
	s_waitcnt vmcnt(12)
	v_add_u32_e32 v17, v17, v2
	s_waitcnt vmcnt(11)
	v_add_u32_e32 v17, v17, v3
	s_waitcnt vmcnt(10)
	v_add_u32_e32 v17, v17, v4
	s_waitcnt vmcnt(9)
	v_add_u32_e32 v17, v17, v5
	s_waitcnt vmcnt(8)
	v_add_u32_e32 v17, v17, v6
	s_waitcnt vmcnt(7)
	v_add_u32_e32 v17, v17, v7
	s_waitcnt vmcnt(6)
	v_add_u32_e32 v17, v17, v8
	s_waitcnt vmcnt(5)
	v_add_u32_e32 v17, v17, v9
	s_waitcnt vmcnt(4)
	v_add_u32_e32 v17, v17, v10
	s_waitcnt vmcnt(3)
	v_add_u32_e32 v17, v17, v11
	s_waitcnt vmcnt(2)
	v_add_u32_e32 v17, v17, v12
	s_waitcnt vmcnt(1)
	v_add_u32_e32 v17, v17, v13
	s_waitcnt vmcnt(0)
	v_add_u32_e32 v17, v17, v14
	v_cmp_eq_u32_e32 vcc, s3, v17
	s_cbranch_vccnz .LBB0_134
	s_and_b32 s44, s33, 0xff
	s_cmp_eq_u32 s44, 0
	s_mov_b64 s[44:45], -1
	s_mov_b64 s[48:49], -1
	s_sleep 0
	s_cbranch_scc0 .LBB0_139
	global_load_dword v17, v16, s[8:9] sc1
	s_waitcnt vmcnt(0)
	v_cmp_eq_u32_e32 vcc, 0, v17
	s_cbranch_vccnz .LBB0_141
	s_mov_b64 s[48:49], 0

; DI unsigned xb_ld(unsigned* p)              { return __hip_atomic_load(p, __ATOMIC_RELAXED, __HIP_MEMORY_SCOPE_AGENT); }
; #define XB_SPIN(cond, bar) do { unsigned _sp = 0; while (cond) { __builtin_amdgcn_s_sleep(1); \
;     if ((++_sp & 255u) == 0u) { if (xb_ld(&(bar)[XB_TMO])) break; if (_sp > XB_SPIN_CAP) { atomicAdd(&(bar)[XB_TMO], 1u); break; } } } } while (0)
; DI void xcd_barrier(const XcdBarrier& b) {
;     ...
;             else XB_SPIN(xb_ld(&bar[XB_TOPGEN]) == tg, bar);
.LBB0_153:
	s_and_b32 s26, s3, 0xff
	s_mov_b64 s[24:25], -1
	s_cmp_lg_u32 s26, 0
	s_mov_b64 s[28:29], -1
	s_sleep 0
	s_cbranch_scc1 .LBB0_156
	global_load_dword v2, v0, s[16:17] sc1
	s_waitcnt vmcnt(0)
	v_cmp_eq_u32_e32 vcc, 0, v2
	s_cbranch_vccnz .LBB0_158
	s_mov_b64 s[28:29], 0
	s_mov_b64 s[26:27], -1

; DI unsigned xb_ld(unsigned* p)              { return __hip_atomic_load(p, __ATOMIC_RELAXED, __HIP_MEMORY_SCOPE_AGENT); }
; #define XB_SPIN(cond, bar) do { unsigned _sp = 0; while (cond) { __builtin_amdgcn_s_sleep(1); \
;     if ((++_sp & 255u) == 0u) { if (xb_ld(&(bar)[XB_TMO])) break; if (_sp > XB_SPIN_CAP) { atomicAdd(&(bar)[XB_TMO], 1u); break; } } } } while (0)
; DI void xcd_barrier(const XcdBarrier& b) {
;     ...
;             XB_SPIN(xb_ld(&bar[XB_XGEN(b.x)]) == gen, bar);
.LBB0_170:
	s_and_b32 s26, s3, 0xff
	s_cmp_lg_u32 s26, 0
	s_mov_b64 s[28:29], -1
	s_sleep 0
	s_cbranch_scc1 .LBB0_173
	global_load_dword v1, v0, s[18:19] sc1
	s_waitcnt vmcnt(0)
	v_cmp_eq_u32_e32 vcc, 0, v1
	s_cbranch_vccnz .LBB0_175
	s_mov_b64 s[28:29], 0
	s_mov_b64 s[26:27], -1

; DI unsigned xb_ld(unsigned* p)              { return __hip_atomic_load(p, __ATOMIC_RELAXED, __HIP_MEMORY_SCOPE_AGENT); }
; DI void xcd_barrier_complete(unsigned* bar, unsigned x, unsigned& nloc, unsigned& nx) {
;     ...
;     for (;;) {
;         sum = 0u; cnt = 0u; mine = 0u;
; #pragma unroll
;         for (unsigned j = 0; j < 16; ++j) { const unsigned c = xb_ld(&bar[XB_XCNT(j)]); sum += c; cnt += (c > 0u) ? 1u : 0u; mine = (j == x) ? c : mine; }
;         if (sum == G) break;
;         __builtin_amdgcn_s_sleep(1);
;         if ((++sp & 255u) == 0u) { if (xb_ld(&bar[XB_TMO])) break; if (sp > XB_SPIN_CAP) { atomicAdd(&bar[XB_TMO], 1u); break; } }
;     }
.LBB0_252:
	v_readlane_b32 s8, v251, 5
	v_readlane_b32 s9, v251, 6
	global_load_dword v0, v1, s[16:17] sc1
	s_mov_b64 s[10:11], -1
	s_waitcnt lgkmcnt(0)
	s_nop 1
	global_load_dword v2, v1, s[8:9] sc1
	v_readlane_b32 s8, v251, 7
	v_readlane_b32 s9, v251, 8
	s_waitcnt vmcnt(0)
	v_add_u32_e32 v17, v2, v0
	s_nop 2
	global_load_dword v3, v1, s[8:9] sc1
	v_readlane_b32 s8, v251, 9
	v_readlane_b32 s9, v251, 10
	s_waitcnt vmcnt(0)
	v_add_u32_e32 v17, v17, v3
	s_nop 2
	global_load_dword v4, v1, s[8:9] sc1
	v_readlane_b32 s8, v251, 11
	v_readlane_b32 s9, v251, 12
	s_waitcnt vmcnt(0)
	v_add_u32_e32 v17, v17, v4
	s_nop 2
	global_load_dword v5, v1, s[8:9] sc1
	v_readlane_b32 s8, v251, 13
	v_readlane_b32 s9, v251, 14
	s_waitcnt vmcnt(0)
	v_add_u32_e32 v17, v17, v5
	s_nop 2
	global_load_dword v6, v1, s[8:9] sc1
	v_readlane_b32 s8, v251, 15
	v_readlane_b32 s9, v251, 16
	s_waitcnt vmcnt(0)
	v_add_u32_e32 v17, v17, v6
	s_nop 2
	global_load_dword v7, v1, s[8:9] sc1
	v_readlane_b32 s8, v251, 17
	v_readlane_b32 s9, v251, 18
	s_waitcnt vmcnt(0)
	v_add_u32_e32 v17, v17, v7
	s_nop 2
	global_load_dword v8, v1, s[8:9] sc1
	v_readlane_b32 s8, v251, 19
	v_readlane_b32 s9, v251, 20
	s_waitcnt vmcnt(0)
	v_add_u32_e32 v17, v17, v8
	s_nop 2
	global_load_dword v9, v1, s[8:9] sc1
	v_readlane_b32 s8, v251, 21
	v_readlane_b32 s9, v251, 22
	s_waitcnt vmcnt(0)
	v_add_u32_e32 v17, v17, v9
	s_nop 2
	global_load_dword v10, v1, s[8:9] sc1
	v_readlane_b32 s8, v251, 23
	v_readlane_b32 s9, v251, 24
	s_waitcnt vmcnt(0)
	v_add_u32_e32 v17, v17, v10
	s_nop 2
	global_load_dword v11, v1, s[8:9] sc1
	v_readlane_b32 s8, v251, 25
	v_readlane_b32 s9, v251, 26
	s_waitcnt vmcnt(0)
	v_add_u32_e32 v17, v17, v11
	s_nop 2
	global_load_dword v12, v1, s[8:9] sc1
	v_readlane_b32 s8, v251, 27
	v_readlane_b32 s9, v251, 28
	s_waitcnt vmcnt(0)
	v_add_u32_e32 v17, v17, v12
	s_nop 2
	global_load_dword v13, v1, s[8:9] sc1
	v_readlane_b32 s8, v251, 29
	v_readlane_b32 s9, v251, 30
	s_waitcnt vmcnt(0)
	v_add_u32_e32 v17, v17, v13
	s_nop 2
	global_load_dword v14, v1, s[8:9] sc1
	v_readlane_b32 s8, v251, 31
	v_readlane_b32 s9, v251, 32
	s_waitcnt vmcnt(0)
	v_add_u32_e32 v17, v17, v14
	s_nop 2
	global_load_dword v15, v1, s[8:9] sc1
	v_readlane_b32 s8, v251, 33
	v_readlane_b32 s9, v251, 34
	s_waitcnt vmcnt(0)
	v_add_u32_e32 v17, v17, v15
	s_nop 2
	global_load_dword v16, v1, s[8:9] sc1
	s_mov_b64 s[8:9], -1
	s_waitcnt vmcnt(0)
	v_add_u32_e32 v17, v17, v16
	v_cmp_eq_u32_e32 vcc, s97, v17
	s_cbranch_vccnz .LBB0_251
	s_and_b32 s8, s14, 0xff
	s_cmp_eq_u32 s8, 0
	s_mov_b64 s[8:9], -1
	s_mov_b64 s[12:13], -1
	s_sleep 0
	s_cbranch_scc0 .LBB0_256
	global_load_dword v17, v1, s[36:37] sc1
	s_waitcnt vmcnt(0)
	v_cmp_eq_u32_e32 vcc, 0, v17
	s_cbranch_vccnz .LBB0_258
	s_mov_b64 s[12:13], 0

; DI unsigned xb_ld(unsigned* p)              { return __hip_atomic_load(p, __ATOMIC_RELAXED, __HIP_MEMORY_SCOPE_AGENT); }
; DI unsigned xb_add(unsigned* p, unsigned v) { return __hip_atomic_fetch_add(p, v, __ATOMIC_RELAXED, __HIP_MEMORY_SCOPE_AGENT); }
; #define XB_SPIN(cond, bar) do { unsigned _sp = 0; while (cond) { __builtin_amdgcn_s_sleep(1); \
;     if ((++_sp & 255u) == 0u) { if (xb_ld(&(bar)[XB_TMO])) break; if (_sp > XB_SPIN_CAP) { atomicAdd(&(bar)[XB_TMO], 1u); break; } } } } while (0)
; DI void xcd_barrier(const XcdBarrier& b) {
;     ...
;             else XB_SPIN(xb_ld(&bar[XB_TOPGEN]) == tg, bar);
;             __builtin_amdgcn_fence(__ATOMIC_ACQUIRE, "agent");
;             xb_add(&bar[XB_XGEN(b.x)], 1u);
;             asm volatile("s_waitcnt vmcnt(0)" ::: "memory");
;         } else {
;             XB_SPIN(xb_ld(&bar[XB_XGEN(b.x)]) == gen, bar);
.LBB0_268:
	s_and_b32 s18, s22, 0xff
	s_mov_b64 s[16:17], -1
	s_cmp_lg_u32 s18, 0
	s_mov_b64 s[20:21], -1
	s_sleep 0
	s_cbranch_scc1 .LBB0_271
	global_load_dword v2, v1, s[36:37] sc1
	s_waitcnt vmcnt(0)
	v_cmp_eq_u32_e32 vcc, 0, v2
	s_cbranch_vccnz .LBB0_273
	s_mov_b64 s[20:21], 0
	s_mov_b64 s[18:19], -1

; DI unsigned xb_ld(unsigned* p)              { return __hip_atomic_load(p, __ATOMIC_RELAXED, __HIP_MEMORY_SCOPE_AGENT); }
; DI void xcd_barrier_complete(unsigned* bar, unsigned x, unsigned& nloc, unsigned& nx) {
;     ...
;     for (;;) {
;         sum = 0u; cnt = 0u; mine = 0u;
; #pragma unroll
;         for (unsigned j = 0; j < 16; ++j) { const unsigned c = xb_ld(&bar[XB_XCNT(j)]); sum += c; cnt += (c > 0u) ? 1u : 0u; mine = (j == x) ? c : mine; }
;         if (sum == G) break;
;         __builtin_amdgcn_s_sleep(1);
;         if ((++sp & 255u) == 0u) { if (xb_ld(&bar[XB_TMO])) break; if (sp > XB_SPIN_CAP) { atomicAdd(&bar[XB_TMO], 1u); break; } }
;     }
.LBB0_536:
	v_readlane_b32 s8, v251, 5
	v_readlane_b32 s9, v251, 6
	global_load_dword v0, v1, s[16:17] sc1
	s_mov_b64 s[10:11], -1
	s_waitcnt lgkmcnt(0)
	s_nop 1
	global_load_dword v2, v1, s[8:9] sc1
	v_readlane_b32 s8, v251, 7
	v_readlane_b32 s9, v251, 8
	s_waitcnt vmcnt(0)
	v_add_u32_e32 v17, v2, v0
	s_nop 2
	global_load_dword v3, v1, s[8:9] sc1
	v_readlane_b32 s8, v251, 9
	v_readlane_b32 s9, v251, 10
	s_waitcnt vmcnt(0)
	v_add_u32_e32 v17, v17, v3
	s_nop 2
	global_load_dword v4, v1, s[8:9] sc1
	v_readlane_b32 s8, v251, 11
	v_readlane_b32 s9, v251, 12
	s_waitcnt vmcnt(0)
	v_add_u32_e32 v17, v17, v4
	s_nop 2
	global_load_dword v5, v1, s[8:9] sc1
	v_readlane_b32 s8, v251, 13
	v_readlane_b32 s9, v251, 14
	s_waitcnt vmcnt(0)
	v_add_u32_e32 v17, v17, v5
	s_nop 2
	global_load_dword v6, v1, s[8:9] sc1
	v_readlane_b32 s8, v251, 15
	v_readlane_b32 s9, v251, 16
	s_waitcnt vmcnt(0)
	v_add_u32_e32 v17, v17, v6
	s_nop 2
	global_load_dword v7, v1, s[8:9] sc1
	v_readlane_b32 s8, v251, 17
	v_readlane_b32 s9, v251, 18
	s_waitcnt vmcnt(0)
	v_add_u32_e32 v17, v17, v7
	s_nop 2
	global_load_dword v8, v1, s[8:9] sc1
	v_readlane_b32 s8, v251, 19
	v_readlane_b32 s9, v251, 20
	s_waitcnt vmcnt(0)
	v_add_u32_e32 v17, v17, v8
	s_nop 2
	global_load_dword v9, v1, s[8:9] sc1
	v_readlane_b32 s8, v251, 21
	v_readlane_b32 s9, v251, 22
	s_waitcnt vmcnt(0)
	v_add_u32_e32 v17, v17, v9
	s_nop 2
	global_load_dword v10, v1, s[8:9] sc1
	v_readlane_b32 s8, v251, 23
	v_readlane_b32 s9, v251, 24
	s_waitcnt vmcnt(0)
	v_add_u32_e32 v17, v17, v10
	s_nop 2
	global_load_dword v11, v1, s[8:9] sc1
	v_readlane_b32 s8, v251, 25
	v_readlane_b32 s9, v251, 26
	s_waitcnt vmcnt(0)
	v_add_u32_e32 v17, v17, v11
	s_nop 2
	global_load_dword v12, v1, s[8:9] sc1
	v_readlane_b32 s8, v251, 27
	v_readlane_b32 s9, v251, 28
	s_waitcnt vmcnt(0)
	v_add_u32_e32 v17, v17, v12
	s_nop 2
	global_load_dword v13, v1, s[8:9] sc1
	v_readlane_b32 s8, v251, 29
	v_readlane_b32 s9, v251, 30
	s_waitcnt vmcnt(0)
	v_add_u32_e32 v17, v17, v13
	s_nop 2
	global_load_dword v14, v1, s[8:9] sc1
	v_readlane_b32 s8, v251, 31
	v_readlane_b32 s9, v251, 32
	s_waitcnt vmcnt(0)
	v_add_u32_e32 v17, v17, v14
	s_nop 2
	global_load_dword v15, v1, s[8:9] sc1
	v_readlane_b32 s8, v251, 33
	v_readlane_b32 s9, v251, 34
	s_waitcnt vmcnt(0)
	v_add_u32_e32 v17, v17, v15
	s_nop 2
	global_load_dword v16, v1, s[8:9] sc1
	s_mov_b64 s[8:9], -1
	s_waitcnt vmcnt(0)
	v_add_u32_e32 v17, v17, v16
	v_cmp_eq_u32_e32 vcc, s97, v17
	s_cbranch_vccnz .LBB0_535
	s_and_b32 s8, s14, 0xff
	s_cmp_eq_u32 s8, 0
	s_mov_b64 s[8:9], -1
	s_mov_b64 s[12:13], -1
	s_sleep 0
	s_cbranch_scc0 .LBB0_540
	global_load_dword v17, v1, s[24:25] sc1
	s_waitcnt vmcnt(0)
	v_cmp_eq_u32_e32 vcc, 0, v17
	s_cbranch_vccnz .LBB0_542
	s_mov_b64 s[12:13], 0

; DI unsigned xb_ld(unsigned* p)              { return __hip_atomic_load(p, __ATOMIC_RELAXED, __HIP_MEMORY_SCOPE_AGENT); }
; DI unsigned xb_add(unsigned* p, unsigned v) { return __hip_atomic_fetch_add(p, v, __ATOMIC_RELAXED, __HIP_MEMORY_SCOPE_AGENT); }
; #define XB_SPIN(cond, bar) do { unsigned _sp = 0; while (cond) { __builtin_amdgcn_s_sleep(1); \
;     if ((++_sp & 255u) == 0u) { if (xb_ld(&(bar)[XB_TMO])) break; if (_sp > XB_SPIN_CAP) { atomicAdd(&(bar)[XB_TMO], 1u); break; } } } } while (0)
; DI void xcd_barrier(const XcdBarrier& b) {
;     ...
;             else XB_SPIN(xb_ld(&bar[XB_TOPGEN]) == tg, bar);
;             __builtin_amdgcn_fence(__ATOMIC_ACQUIRE, "agent");
;             xb_add(&bar[XB_XGEN(b.x)], 1u);
;             asm volatile("s_waitcnt vmcnt(0)" ::: "memory");
;         } else {
;             XB_SPIN(xb_ld(&bar[XB_XGEN(b.x)]) == gen, bar);
.LBB0_552:
	s_and_b32 s18, s22, 0xff
	s_mov_b64 s[16:17], -1
	s_cmp_lg_u32 s18, 0
	s_mov_b64 s[20:21], -1
	s_sleep 0
	s_cbranch_scc1 .LBB0_555
	global_load_dword v2, v1, s[24:25] sc1
	s_waitcnt vmcnt(0)
	v_cmp_eq_u32_e32 vcc, 0, v2
	s_cbranch_vccnz .LBB0_557
	s_mov_b64 s[20:21], 0
	s_mov_b64 s[18:19], -1
